# v10 + v_mov_b64 accumulator zeroing + no mid-block setprio flips + dropped redundant mid-segment lgkmcnt(0) in the A1 K-loop
# speedup vs baseline: 1.0055x; 1.0055x over previous
.LBB0_803:
	s_add_u32 s12, s28, s8
	s_addc_u32 s13, s29, s9
	s_add_u32 s12, s12, 0x100
	s_addc_u32 s13, s13, 0
	s_add_u32 s81, s84, s8
	s_addc_u32 s83, s85, s9
	s_add_i32 s95, 0, 0x10000
	s_cmpk_eq_i32 s8, 0xf00
	s_cselect_b32 s37, s27, s13
	s_cselect_b32 s36, s42, s12
	s_cselect_b32 s13, s25, s83
	s_cselect_b32 s12, s43, s81
	s_add_i32 s81, 0, 0x14000
	v_add_u32_e32 v148, s95, v207
	v_add_u32_e32 v176, s81, v207
	ds_read_b128 v[136:139], v148
	ds_read_b128 v[140:143], v148 offset:1024
	ds_read_b128 v[144:147], v148 offset:2048
	ds_read_b128 v[148:151], v148 offset:3072
	ds_read_b128 v[152:155], v176
	ds_read_b128 v[156:159], v176 offset:1024
	ds_read_b128 v[160:163], v176 offset:2048
	ds_read_b128 v[176:179], v176 offset:3072
	v_lshl_add_u64 v[196:197], v[132:133], 0, s[8:9]
	s_add_i32 m0, s75, 0xc000
	ds_read_b128 v[180:183], v209
	ds_read_b128 v[184:187], v209 offset:1024
	ds_read_b128 v[188:191], v209 offset:2048
	ds_read_b128 v[192:195], v209 offset:3072
	ds_read_b128 v[212:215], v209 offset:4096
	ds_read_b128 v[226:229], v209 offset:5120
	ds_read_b128 v[230:233], v209 offset:6144
	ds_read_b128 v[234:237], v209 offset:7168
	global_load_lds_dwordx4 v[196:197], off
	v_lshl_add_u64 v[196:197], v[134:135], 0, s[8:9]
	s_add_i32 m0, s75, 0xe000
	s_nop 0
	global_load_lds_dwordx4 v[196:197], off
	s_waitcnt vmcnt(8)
	s_waitcnt lgkmcnt(0)
	s_setprio 1
	s_barrier
	v_mfma_f32_16x16x32_bf16 v[8:11], v[136:139], v[180:183], v[8:11]
	v_mfma_f32_16x16x32_bf16 v[128:131], v[144:147], v[180:183], v[128:131]
	v_mfma_f32_16x16x32_bf16 v[124:127], v[136:139], v[188:191], v[124:127]
	v_mfma_f32_16x16x32_bf16 v[120:123], v[144:147], v[188:191], v[120:123]
	v_mfma_f32_16x16x32_bf16 v[116:119], v[136:139], v[212:215], v[116:119]
	v_mfma_f32_16x16x32_bf16 v[112:115], v[144:147], v[212:215], v[112:115]
	v_mfma_f32_16x16x32_bf16 v[108:111], v[136:139], v[230:233], v[108:111]
	v_mfma_f32_16x16x32_bf16 v[104:107], v[144:147], v[230:233], v[104:107]
	v_mfma_f32_16x16x32_bf16 v[8:11], v[140:143], v[184:187], v[8:11]
	v_mfma_f32_16x16x32_bf16 v[128:131], v[148:151], v[184:187], v[128:131]
	v_mfma_f32_16x16x32_bf16 v[124:127], v[140:143], v[192:195], v[124:127]
	v_mfma_f32_16x16x32_bf16 v[120:123], v[148:151], v[192:195], v[120:123]
	v_mfma_f32_16x16x32_bf16 v[116:119], v[140:143], v[226:229], v[116:119]
	v_mfma_f32_16x16x32_bf16 v[112:115], v[148:151], v[226:229], v[112:115]
	v_mfma_f32_16x16x32_bf16 v[108:111], v[140:143], v[234:237], v[108:111]
	v_mfma_f32_16x16x32_bf16 v[104:107], v[148:151], v[234:237], v[104:107]
	v_mfma_f32_16x16x32_bf16 v[100:103], v[152:155], v[180:183], v[100:103]
	v_mfma_f32_16x16x32_bf16 v[96:99], v[160:163], v[180:183], v[96:99]
	v_mfma_f32_16x16x32_bf16 v[92:95], v[152:155], v[188:191], v[92:95]
	v_mfma_f32_16x16x32_bf16 v[88:91], v[160:163], v[188:191], v[88:91]
	v_mfma_f32_16x16x32_bf16 v[84:87], v[152:155], v[212:215], v[84:87]
	v_mfma_f32_16x16x32_bf16 v[80:83], v[160:163], v[212:215], v[80:83]
	v_mfma_f32_16x16x32_bf16 v[76:79], v[152:155], v[230:233], v[76:79]
	v_mfma_f32_16x16x32_bf16 v[72:75], v[160:163], v[230:233], v[72:75]
	v_mfma_f32_16x16x32_bf16 v[100:103], v[156:159], v[184:187], v[100:103]
	v_mfma_f32_16x16x32_bf16 v[96:99], v[176:179], v[184:187], v[96:99]
	v_mfma_f32_16x16x32_bf16 v[92:95], v[156:159], v[192:195], v[92:95]
	v_mfma_f32_16x16x32_bf16 v[88:91], v[176:179], v[192:195], v[88:91]
	v_mfma_f32_16x16x32_bf16 v[84:87], v[156:159], v[226:229], v[84:87]
	v_mfma_f32_16x16x32_bf16 v[80:83], v[176:179], v[226:229], v[80:83]
	v_mfma_f32_16x16x32_bf16 v[76:79], v[156:159], v[234:237], v[76:79]
	v_mfma_f32_16x16x32_bf16 v[72:75], v[176:179], v[234:237], v[72:75]
	s_setprio 0
	s_barrier
	s_add_i32 s83, s95, s74
	v_lshl_add_u64 v[196:197], s[12:13], 0, v[164:165]
	s_mov_b32 m0, s83
	ds_read_b128 v[180:183], v209 offset:16384
	ds_read_b128 v[184:187], v209 offset:17408
	ds_read_b128 v[188:191], v209 offset:18432
	ds_read_b128 v[192:195], v209 offset:19456
	ds_read_b128 v[212:215], v209 offset:20480
	ds_read_b128 v[226:229], v209 offset:21504
	ds_read_b128 v[230:233], v209 offset:22528
	ds_read_b128 v[234:237], v209 offset:23552
	global_load_lds_dwordx4 v[196:197], off
	s_add_i32 m0, s83, 0x2000
	s_add_u32 vcc_lo, s12, 0x80000
	v_lshl_add_u64 v[198:199], s[12:13], 0, v[168:169]
	s_addc_u32 vcc_hi, s13, 0
	s_add_i32 s81, s81, s74
	global_load_lds_dwordx4 v[198:199], off
	v_lshl_add_u64 v[200:201], vcc, 0, v[164:165]
	s_mov_b32 m0, s81
	v_lshl_add_u64 v[202:203], s[36:37], 0, v[166:167]
	global_load_lds_dwordx4 v[200:201], off
	v_lshl_add_u64 v[200:201], vcc, 0, v[168:169]
	s_add_i32 m0, s81, 0x2000
	s_nop 0
	global_load_lds_dwordx4 v[200:201], off
	v_lshl_add_u64 v[200:201], s[36:37], 0, v[0:1]
	s_mov_b32 m0, s75
	s_nop 0
	global_load_lds_dwordx4 v[200:201], off
	s_mov_b32 m0, s15
	s_nop 0
	global_load_lds_dwordx4 v[202:203], off
	s_waitcnt vmcnt(8)
	s_waitcnt lgkmcnt(0)
	s_setprio 1
	s_barrier
	v_mfma_f32_16x16x32_bf16 v[68:71], v[136:139], v[180:183], v[68:71]
	v_mfma_f32_16x16x32_bf16 v[64:67], v[144:147], v[180:183], v[64:67]
	v_mfma_f32_16x16x32_bf16 v[60:63], v[136:139], v[188:191], v[60:63]
	v_mfma_f32_16x16x32_bf16 v[56:59], v[144:147], v[188:191], v[56:59]
	v_mfma_f32_16x16x32_bf16 v[52:55], v[136:139], v[212:215], v[52:55]
	v_mfma_f32_16x16x32_bf16 v[48:51], v[144:147], v[212:215], v[48:51]
	v_mfma_f32_16x16x32_bf16 v[44:47], v[136:139], v[230:233], v[44:47]
	v_mfma_f32_16x16x32_bf16 v[40:43], v[144:147], v[230:233], v[40:43]
	v_mfma_f32_16x16x32_bf16 v[68:71], v[140:143], v[184:187], v[68:71]
	v_mfma_f32_16x16x32_bf16 v[64:67], v[148:151], v[184:187], v[64:67]
	v_mfma_f32_16x16x32_bf16 v[60:63], v[140:143], v[192:195], v[60:63]
	v_mfma_f32_16x16x32_bf16 v[56:59], v[148:151], v[192:195], v[56:59]
	v_mfma_f32_16x16x32_bf16 v[52:55], v[140:143], v[226:229], v[52:55]
	v_mfma_f32_16x16x32_bf16 v[48:51], v[148:151], v[226:229], v[48:51]
	v_mfma_f32_16x16x32_bf16 v[44:47], v[140:143], v[234:237], v[44:47]
	v_mfma_f32_16x16x32_bf16 v[40:43], v[148:151], v[234:237], v[40:43]
	v_mfma_f32_16x16x32_bf16 v[36:39], v[152:155], v[180:183], v[36:39]
	v_mfma_f32_16x16x32_bf16 v[32:35], v[160:163], v[180:183], v[32:35]
	v_mfma_f32_16x16x32_bf16 v[28:31], v[152:155], v[188:191], v[28:31]
	v_mfma_f32_16x16x32_bf16 v[24:27], v[160:163], v[188:191], v[24:27]
	v_mfma_f32_16x16x32_bf16 v[20:23], v[152:155], v[212:215], v[20:23]
	v_mfma_f32_16x16x32_bf16 v[16:19], v[160:163], v[212:215], v[16:19]
	v_mfma_f32_16x16x32_bf16 v[12:15], v[152:155], v[230:233], v[12:15]
	v_mfma_f32_16x16x32_bf16 v[4:7], v[160:163], v[230:233], v[4:7]
	v_mfma_f32_16x16x32_bf16 v[36:39], v[156:159], v[184:187], v[36:39]
	v_mfma_f32_16x16x32_bf16 v[32:35], v[176:179], v[184:187], v[32:35]
	v_mfma_f32_16x16x32_bf16 v[28:31], v[156:159], v[192:195], v[28:31]
	v_mfma_f32_16x16x32_bf16 v[24:27], v[176:179], v[192:195], v[24:27]
	v_mfma_f32_16x16x32_bf16 v[20:23], v[156:159], v[226:229], v[20:23]
	v_mfma_f32_16x16x32_bf16 v[16:19], v[176:179], v[226:229], v[16:19]
	v_mfma_f32_16x16x32_bf16 v[12:15], v[156:159], v[234:237], v[12:15]
	v_mfma_f32_16x16x32_bf16 v[4:7], v[176:179], v[234:237], v[4:7]
	s_setprio 0
	s_barrier
	s_add_i32 s81, 0, 0x18000
	s_add_i32 s83, 0, 0x1c000
	v_add_u32_e32 v148, s81, v207
	v_add_u32_e32 v176, s83, v207
	ds_read_b128 v[136:139], v148
	ds_read_b128 v[140:143], v148 offset:1024
	ds_read_b128 v[144:147], v148 offset:2048
	ds_read_b128 v[148:151], v148 offset:3072
	ds_read_b128 v[152:155], v176
	ds_read_b128 v[156:159], v176 offset:1024
	ds_read_b128 v[160:163], v176 offset:2048
	ds_read_b128 v[176:179], v176 offset:3072
	s_add_u32 s36, s36, 0x80000
	s_addc_u32 s37, s37, 0
	s_mov_b32 m0, s38
	v_lshl_add_u64 v[216:217], s[36:37], 0, v[0:1]
	ds_read_b128 v[180:183], v209 offset:32768
	ds_read_b128 v[184:187], v209 offset:33792
	ds_read_b128 v[188:191], v209 offset:34816
	ds_read_b128 v[192:195], v209 offset:35840
	ds_read_b128 v[212:215], v209 offset:36864
	ds_read_b128 v[226:229], v209 offset:37888
	ds_read_b128 v[230:233], v209 offset:38912
	ds_read_b128 v[234:237], v209 offset:39936
	global_load_lds_dwordx4 v[216:217], off
	v_lshl_add_u64 v[216:217], s[36:37], 0, v[166:167]
	s_mov_b32 m0, s39
	s_nop 0
	global_load_lds_dwordx4 v[216:217], off
	s_waitcnt vmcnt(8)
	s_waitcnt lgkmcnt(0)
	s_setprio 1
	s_barrier
	v_mfma_f32_16x16x32_bf16 v[8:11], v[136:139], v[180:183], v[8:11]
	v_mfma_f32_16x16x32_bf16 v[128:131], v[144:147], v[180:183], v[128:131]
	v_mfma_f32_16x16x32_bf16 v[124:127], v[136:139], v[188:191], v[124:127]
	v_mfma_f32_16x16x32_bf16 v[120:123], v[144:147], v[188:191], v[120:123]
	v_mfma_f32_16x16x32_bf16 v[116:119], v[136:139], v[212:215], v[116:119]
	v_mfma_f32_16x16x32_bf16 v[112:115], v[144:147], v[212:215], v[112:115]
	v_mfma_f32_16x16x32_bf16 v[108:111], v[136:139], v[230:233], v[108:111]
	v_mfma_f32_16x16x32_bf16 v[104:107], v[144:147], v[230:233], v[104:107]
	v_mfma_f32_16x16x32_bf16 v[8:11], v[140:143], v[184:187], v[8:11]
	v_mfma_f32_16x16x32_bf16 v[128:131], v[148:151], v[184:187], v[128:131]
	v_mfma_f32_16x16x32_bf16 v[124:127], v[140:143], v[192:195], v[124:127]
	v_mfma_f32_16x16x32_bf16 v[120:123], v[148:151], v[192:195], v[120:123]
	v_mfma_f32_16x16x32_bf16 v[116:119], v[140:143], v[226:229], v[116:119]
	v_mfma_f32_16x16x32_bf16 v[112:115], v[148:151], v[226:229], v[112:115]
	v_mfma_f32_16x16x32_bf16 v[108:111], v[140:143], v[234:237], v[108:111]
	v_mfma_f32_16x16x32_bf16 v[104:107], v[148:151], v[234:237], v[104:107]
	v_mfma_f32_16x16x32_bf16 v[100:103], v[152:155], v[180:183], v[100:103]
	v_mfma_f32_16x16x32_bf16 v[96:99], v[160:163], v[180:183], v[96:99]
	v_mfma_f32_16x16x32_bf16 v[92:95], v[152:155], v[188:191], v[92:95]
	v_mfma_f32_16x16x32_bf16 v[88:91], v[160:163], v[188:191], v[88:91]
	v_mfma_f32_16x16x32_bf16 v[84:87], v[152:155], v[212:215], v[84:87]
	v_mfma_f32_16x16x32_bf16 v[80:83], v[160:163], v[212:215], v[80:83]
	v_mfma_f32_16x16x32_bf16 v[76:79], v[152:155], v[230:233], v[76:79]
	v_mfma_f32_16x16x32_bf16 v[72:75], v[160:163], v[230:233], v[72:75]
	v_mfma_f32_16x16x32_bf16 v[100:103], v[156:159], v[184:187], v[100:103]
	v_mfma_f32_16x16x32_bf16 v[96:99], v[176:179], v[184:187], v[96:99]
	v_mfma_f32_16x16x32_bf16 v[92:95], v[156:159], v[192:195], v[92:95]
	v_mfma_f32_16x16x32_bf16 v[88:91], v[176:179], v[192:195], v[88:91]
	v_mfma_f32_16x16x32_bf16 v[84:87], v[156:159], v[226:229], v[84:87]
	v_mfma_f32_16x16x32_bf16 v[80:83], v[176:179], v[226:229], v[80:83]
	v_mfma_f32_16x16x32_bf16 v[76:79], v[156:159], v[234:237], v[76:79]
	v_mfma_f32_16x16x32_bf16 v[72:75], v[176:179], v[234:237], v[72:75]
	s_setprio 0
	s_barrier
	s_add_i32 s36, s81, s74
	v_lshl_add_u64 v[196:197], v[196:197], 0, s[70:71]
	s_mov_b32 m0, s36
	ds_read_b128 v[180:183], v209 offset:49152
	ds_read_b128 v[184:187], v209 offset:50176
	ds_read_b128 v[188:191], v209 offset:51200
	ds_read_b128 v[192:195], v209 offset:52224
	ds_read_b128 v[212:215], v209 offset:53248
	ds_read_b128 v[226:229], v209 offset:54272
	ds_read_b128 v[230:233], v209 offset:55296
	ds_read_b128 v[234:237], v209 offset:56320
	global_load_lds_dwordx4 v[196:197], off
	s_add_i32 m0, s36, 0x2000
	s_add_u32 s12, s12, 0x80080
	v_lshl_add_u64 v[196:197], v[198:199], 0, s[70:71]
	s_addc_u32 s13, s13, 0
	s_add_i32 s36, s83, s74
	global_load_lds_dwordx4 v[196:197], off
	v_lshl_add_u64 v[196:197], s[12:13], 0, v[164:165]
	s_mov_b32 m0, s36
	s_nop 0
	global_load_lds_dwordx4 v[196:197], off
	v_lshl_add_u64 v[196:197], s[12:13], 0, v[168:169]
	s_add_i32 m0, s36, 0x2000
	s_nop 0
	global_load_lds_dwordx4 v[196:197], off
	v_lshl_add_u64 v[196:197], v[200:201], 0, s[70:71]
	s_mov_b32 m0, s51
	s_nop 0
	global_load_lds_dwordx4 v[196:197], off
	v_lshl_add_u64 v[196:197], v[202:203], 0, s[70:71]
	s_mov_b32 m0, s92
	s_nop 0
	global_load_lds_dwordx4 v[196:197], off
	s_waitcnt vmcnt(8)
	s_waitcnt lgkmcnt(0)
	s_setprio 1
	s_barrier
	v_mfma_f32_16x16x32_bf16 v[68:71], v[136:139], v[180:183], v[68:71]
	v_mfma_f32_16x16x32_bf16 v[64:67], v[144:147], v[180:183], v[64:67]
	v_mfma_f32_16x16x32_bf16 v[60:63], v[136:139], v[188:191], v[60:63]
	v_mfma_f32_16x16x32_bf16 v[56:59], v[144:147], v[188:191], v[56:59]
	v_mfma_f32_16x16x32_bf16 v[52:55], v[136:139], v[212:215], v[52:55]
	v_mfma_f32_16x16x32_bf16 v[48:51], v[144:147], v[212:215], v[48:51]
	v_mfma_f32_16x16x32_bf16 v[44:47], v[136:139], v[230:233], v[44:47]
	v_mfma_f32_16x16x32_bf16 v[40:43], v[144:147], v[230:233], v[40:43]
	v_mfma_f32_16x16x32_bf16 v[68:71], v[140:143], v[184:187], v[68:71]
	v_mfma_f32_16x16x32_bf16 v[64:67], v[148:151], v[184:187], v[64:67]
	v_mfma_f32_16x16x32_bf16 v[60:63], v[140:143], v[192:195], v[60:63]
	v_mfma_f32_16x16x32_bf16 v[56:59], v[148:151], v[192:195], v[56:59]
	v_mfma_f32_16x16x32_bf16 v[52:55], v[140:143], v[226:229], v[52:55]
	v_mfma_f32_16x16x32_bf16 v[48:51], v[148:151], v[226:229], v[48:51]
	v_mfma_f32_16x16x32_bf16 v[44:47], v[140:143], v[234:237], v[44:47]
	v_mfma_f32_16x16x32_bf16 v[40:43], v[148:151], v[234:237], v[40:43]
	v_mfma_f32_16x16x32_bf16 v[36:39], v[152:155], v[180:183], v[36:39]
	v_mfma_f32_16x16x32_bf16 v[32:35], v[160:163], v[180:183], v[32:35]
	v_mfma_f32_16x16x32_bf16 v[28:31], v[152:155], v[188:191], v[28:31]
	v_mfma_f32_16x16x32_bf16 v[24:27], v[160:163], v[188:191], v[24:27]
	v_mfma_f32_16x16x32_bf16 v[20:23], v[152:155], v[212:215], v[20:23]
	v_mfma_f32_16x16x32_bf16 v[16:19], v[160:163], v[212:215], v[16:19]
	v_mfma_f32_16x16x32_bf16 v[12:15], v[152:155], v[230:233], v[12:15]
	v_mfma_f32_16x16x32_bf16 v[4:7], v[160:163], v[230:233], v[4:7]
	v_mfma_f32_16x16x32_bf16 v[36:39], v[156:159], v[184:187], v[36:39]
	v_mfma_f32_16x16x32_bf16 v[32:35], v[176:179], v[184:187], v[32:35]
	v_mfma_f32_16x16x32_bf16 v[28:31], v[156:159], v[192:195], v[28:31]
	v_mfma_f32_16x16x32_bf16 v[24:27], v[176:179], v[192:195], v[24:27]
	v_mfma_f32_16x16x32_bf16 v[20:23], v[156:159], v[226:229], v[20:23]
	v_mfma_f32_16x16x32_bf16 v[16:19], v[176:179], v[226:229], v[16:19]
	v_mfma_f32_16x16x32_bf16 v[12:15], v[156:159], v[234:237], v[12:15]
	v_mfma_f32_16x16x32_bf16 v[4:7], v[176:179], v[234:237], v[4:7]
	s_setprio 0
	s_barrier
	s_add_i32 s52, s52, 2
	s_add_u32 s8, s8, 0x100
	s_addc_u32 s9, s9, 0
	s_cmp_gt_u32 s52, 29
	s_cbranch_scc0 .LBB0_803
	s_and_b64 vcc, exec, s[22:23]
	s_cbranch_vccz .LBB0_806
	s_barrier
